# P7 first K-loop trip peeled too (C=0 accumulator start; single-trip units skip the loop)
# speedup vs baseline: 1.0028x; 1.0028x over previous
; #define PG8_STAGE(bufoff, gbase, voff) do { _Pragma("unroll") for (int _i = 0; _i < 2; ++_i) \
;         __builtin_amdgcn_global_load_lds((const unsigned*)((const char*)(gbase) + (voff)[_i]), (PG8_LAS unsigned*)(lds + (bufoff) + ldsw + _i * 8192), 16, 0, 0); } while (0)
; #define PG8_LDA(dst, b, h) do { _Pragma("unroll") for (int m = 0; m < 4; ++m) _Pragma("unroll") for (int k = 0; k < 2; ++k) dst[m][k] = *(const PG8_LAS bf16x8*)(lds + PG8_SA(b, h) + aoff + m * 2048 + k * 1024); } while (0)
; #define PG8_LDB(dst, b, h) do { _Pragma("unroll") for (int n = 0; n < 2; ++n) _Pragma("unroll") for (int k = 0; k < 2; ++k) dst[n][k] = *(const PG8_LAS bf16x8*)(lds + PG8_SB(b, h) + boff + n * 2048 + k * 1024); } while (0)
; #define PG8_SCHED __builtin_amdgcn_sched_barrier(0)
; template <class Epi, class Sched, bool ALIGN_EPI = false, bool SP2 = false>
; __device__ __forceinline__ void gemm_phase(PG8_LAS unsigned char* lds, const Gemm g, const Sched& S, const Epi& E) {
;     ...
;         const bool has_next = S.next(ui + 1, nxt);
;         const char* nA = has_next ? (const char*)g.A + (size_t)nxt.pm * tstep : cA; const char* nB = has_next ? (const char*)g.Bt + (size_t)nxt.pn * tstep : cB;
; #pragma nounroll
;         for (int t = 0; t < nt; t += 2) {
;             const bool last = (t == nt - 2);
;             const char* a1 = cA + (size_t)(t + 1) * kstep;
;             const char* a2 = last ? nA : cA + (size_t)(t + 2) * kstep; const char* b2 = last ? nB : cB + (size_t)(t + 2) * kstep;
;             const char* a3 = a2 + kstep; const char* b3 = b2 + kstep;
;             if (last && has_next) S.a_ready(nxt);
;             if constexpr (SP2) {
;             PG8_LDB(B0, 0, 0); PG8_LDB(B1, 0, 1); PG8_SCHED; PG8_LDA(At, 0, 0); PG8_STAGE(PG8_SA(1, 1), a1 + hstep, voffA);
.LBB0_864:
	s_cmp_gt_i32 s33, 7
	s_cselect_b32 s98, 2, 0
	s_add_i32 s101, s98, -2
	s_add_u32 s4, s8, 0x18080
	s_addc_u32 s5, s9, 0
	s_add_u32 s35, s6, 0x100
	s_addc_u32 s70, s7, 0
	s_mov_b32 s71, -2
	ds_read_b128 v[148:151], v170
	ds_read_b128 v[152:155], v170 offset:1024
	ds_read_b128 v[156:159], v170 offset:2048
	ds_read_b128 v[160:163], v170 offset:3072
	ds_read_b128 v[164:167], v171
	ds_read_b128 v[176:179], v171 offset:1024
	ds_read_b128 v[180:183], v171 offset:2048
	ds_read_b128 v[184:187], v171 offset:3072
	s_add_u32 s6, s4, 0xfffe8080
	s_addc_u32 s7, s5, -1
	s_cmp_eq_u32 s71, s101
	s_cselect_b32 s9, s29, s7
	s_cselect_b32 s8, s28, s6
	s_cselect_b32 s7, s31, s70
	s_cselect_b32 s6, s30, s35

; #define PG8_STAGE(bufoff, gbase, voff) do { _Pragma("unroll") for (int _i = 0; _i < 2; ++_i) \
;         __builtin_amdgcn_global_load_lds((const unsigned*)((const char*)(gbase) + (voff)[_i]), (PG8_LAS unsigned*)(lds + (bufoff) + ldsw + _i * 8192), 16, 0, 0); } while (0)
; #define PG8_LDA(dst, b, h) do { _Pragma("unroll") for (int m = 0; m < 4; ++m) _Pragma("unroll") for (int k = 0; k < 2; ++k) dst[m][k] = *(const PG8_LAS bf16x8*)(lds + PG8_SA(b, h) + aoff + m * 2048 + k * 1024); } while (0)
; #define PG8_LDB(dst, b, h) do { _Pragma("unroll") for (int n = 0; n < 2; ++n) _Pragma("unroll") for (int k = 0; k < 2; ++k) dst[n][k] = *(const PG8_LAS bf16x8*)(lds + PG8_SB(b, h) + boff + n * 2048 + k * 1024); } while (0)
; #define PG8_MMA(ai, bj, At, Bt) do { __builtin_amdgcn_s_setprio(1); _Pragma("unroll") for (int m = 0; m < 4; ++m) _Pragma("unroll") for (int n = 0; n < 2; ++n) _Pragma("unroll") for (int k = 0; k < 2; ++k) \
;         acc[ai][bj][m][n] = __builtin_amdgcn_mfma_f32_16x16x32_bf16(Bt[n][k], At[m][k], acc[ai][bj][m][n], 0, 0, 0); __builtin_amdgcn_s_setprio(0); } while (0)
; #define PG8_WAIT_V(n) asm volatile("s_waitcnt vmcnt(" #n ")" ::: "memory")
; #define PG8_WAIT_L(n) asm volatile("s_waitcnt lgkmcnt(" #n ")" ::: "memory")
; #define PG8_BAR __builtin_amdgcn_s_barrier()
; #define PG8_SCHED __builtin_amdgcn_sched_barrier(0)
; template <class Epi, class Sched, bool ALIGN_EPI = false, bool SP2 = false>
; __device__ __forceinline__ void gemm_phase(PG8_LAS unsigned char* lds, const Gemm g, const Sched& S, const Epi& E) {
;     ...
;             PG8_LDB(B0, 0, 0); PG8_LDB(B1, 0, 1); PG8_SCHED; PG8_LDA(At, 0, 0); PG8_STAGE(PG8_SA(1, 1), a1 + hstep, voffA);
;             PG8_WAIT_V(8); PG8_WAIT_L(0); PG8_BAR; PG8_MMA(0, 0, At, B0); PG8_MMA(0, 1, At, B1); PG8_BAR; PG8_SCHED;
	v_lshl_add_u64 v[220:221], s[4:5], 0, v[140:141]
	s_add_i32 m0, s43, 0xc000
	ds_read_b128 v[188:191], v174
	ds_read_b128 v[192:195], v174 offset:1024
	ds_read_b128 v[196:199], v174 offset:2048
	ds_read_b128 v[200:203], v174 offset:3072
	ds_read_b128 v[204:207], v174 offset:4096
	ds_read_b128 v[208:211], v174 offset:5120
	ds_read_b128 v[212:215], v174 offset:6144
	ds_read_b128 v[216:219], v174 offset:7168
	global_load_lds_dwordx4 v[220:221], off
	v_lshl_add_u64 v[220:221], s[4:5], 0, v[142:143]
	s_add_i32 m0, s43, 0xe000
	s_nop 0
	global_load_lds_dwordx4 v[220:221], off
	s_waitcnt vmcnt(8)
	s_waitcnt lgkmcnt(0)
	s_barrier
	s_setprio 1
	s_waitcnt lgkmcnt(0)
	v_mfma_f32_16x16x32_bf16 v[126:129], v[148:151], v[188:191], 0
	v_mfma_f32_16x16x32_bf16 v[122:125], v[156:159], v[188:191], 0
	v_mfma_f32_16x16x32_bf16 v[110:113], v[148:151], v[196:199], 0
	v_mfma_f32_16x16x32_bf16 v[106:109], v[156:159], v[196:199], 0
	v_mfma_f32_16x16x32_bf16 v[94:97], v[148:151], v[204:207], 0
	v_mfma_f32_16x16x32_bf16 v[90:93], v[156:159], v[204:207], 0
	v_mfma_f32_16x16x32_bf16 v[78:81], v[148:151], v[212:215], 0
	v_mfma_f32_16x16x32_bf16 v[74:77], v[156:159], v[212:215], 0
	v_mfma_f32_16x16x32_bf16 v[126:129], v[152:155], v[192:195], v[126:129]
	v_mfma_f32_16x16x32_bf16 v[122:125], v[160:163], v[192:195], v[122:125]
	v_mfma_f32_16x16x32_bf16 v[110:113], v[152:155], v[200:203], v[110:113]
	v_mfma_f32_16x16x32_bf16 v[106:109], v[160:163], v[200:203], v[106:109]
	v_mfma_f32_16x16x32_bf16 v[94:97], v[152:155], v[208:211], v[94:97]
	v_mfma_f32_16x16x32_bf16 v[90:93], v[160:163], v[208:211], v[90:93]
	v_mfma_f32_16x16x32_bf16 v[78:81], v[152:155], v[216:219], v[78:81]
	v_mfma_f32_16x16x32_bf16 v[74:77], v[160:163], v[216:219], v[74:77]
	s_setprio 0
	s_setprio 1
	v_mfma_f32_16x16x32_bf16 v[118:121], v[164:167], v[188:191], 0
	v_mfma_f32_16x16x32_bf16 v[114:117], v[180:183], v[188:191], 0
	v_mfma_f32_16x16x32_bf16 v[102:105], v[164:167], v[196:199], 0
	v_mfma_f32_16x16x32_bf16 v[98:101], v[180:183], v[196:199], 0
	v_mfma_f32_16x16x32_bf16 v[86:89], v[164:167], v[204:207], 0
	v_mfma_f32_16x16x32_bf16 v[82:85], v[180:183], v[204:207], 0
	v_mfma_f32_16x16x32_bf16 v[70:73], v[164:167], v[212:215], 0
	v_mfma_f32_16x16x32_bf16 v[66:69], v[180:183], v[212:215], 0
	v_mfma_f32_16x16x32_bf16 v[118:121], v[176:179], v[192:195], v[118:121]
	v_mfma_f32_16x16x32_bf16 v[114:117], v[184:187], v[192:195], v[114:117]
	v_mfma_f32_16x16x32_bf16 v[102:105], v[176:179], v[200:203], v[102:105]
	v_mfma_f32_16x16x32_bf16 v[98:101], v[184:187], v[200:203], v[98:101]
	v_mfma_f32_16x16x32_bf16 v[86:89], v[176:179], v[208:211], v[86:89]
	v_mfma_f32_16x16x32_bf16 v[82:85], v[184:187], v[208:211], v[82:85]
	v_mfma_f32_16x16x32_bf16 v[70:73], v[176:179], v[216:219], v[70:73]
	v_mfma_f32_16x16x32_bf16 v[66:69], v[184:187], v[216:219], v[66:69]
	s_setprio 0
	s_barrier

; #define PG8_STAGE(bufoff, gbase, voff) do { _Pragma("unroll") for (int _i = 0; _i < 2; ++_i) \
;         __builtin_amdgcn_global_load_lds((const unsigned*)((const char*)(gbase) + (voff)[_i]), (PG8_LAS unsigned*)(lds + (bufoff) + ldsw + _i * 8192), 16, 0, 0); } while (0)
; #define PG8_LDA(dst, b, h) do { _Pragma("unroll") for (int m = 0; m < 4; ++m) _Pragma("unroll") for (int k = 0; k < 2; ++k) dst[m][k] = *(const PG8_LAS bf16x8*)(lds + PG8_SA(b, h) + aoff + m * 2048 + k * 1024); } while (0)
; #define PG8_MMA(ai, bj, At, Bt) do { __builtin_amdgcn_s_setprio(1); _Pragma("unroll") for (int m = 0; m < 4; ++m) _Pragma("unroll") for (int n = 0; n < 2; ++n) _Pragma("unroll") for (int k = 0; k < 2; ++k) \
;         acc[ai][bj][m][n] = __builtin_amdgcn_mfma_f32_16x16x32_bf16(Bt[n][k], At[m][k], acc[ai][bj][m][n], 0, 0, 0); __builtin_amdgcn_s_setprio(0); } while (0)
; #define PG8_WAIT_V(n) asm volatile("s_waitcnt vmcnt(" #n ")" ::: "memory")
; #define PG8_WAIT_L(n) asm volatile("s_waitcnt lgkmcnt(" #n ")" ::: "memory")
; #define PG8_BAR __builtin_amdgcn_s_barrier()
; #define PG8_SCHED __builtin_amdgcn_sched_barrier(0)
; template <class Epi, class Sched, bool ALIGN_EPI = false, bool SP2 = false>
; __device__ __forceinline__ void gemm_phase(PG8_LAS unsigned char* lds, const Gemm g, const Sched& S, const Epi& E) {
;     ...
;             PG8_LDA(At, 0, 1); PG8_STAGE(PG8_SB(0, 0), b2, voffB); PG8_STAGE(PG8_SB(0, 1), b2 + hstep, voffB); PG8_STAGE(PG8_SA(0, 0), a2, voffA);
;             PG8_WAIT_V(8); PG8_WAIT_L(0); PG8_BAR; PG8_MMA(1, 0, At, B0); PG8_MMA(1, 1, At, B1); PG8_BAR; PG8_SCHED;
	s_add_i32 s72, s66, s42
	v_lshl_add_u64 v[220:221], s[6:7], 0, v[132:133]
	s_mov_b32 m0, s72
	ds_read_b128 v[188:191], v174 offset:16384
	ds_read_b128 v[192:195], v174 offset:17408
	ds_read_b128 v[196:199], v174 offset:18432
	ds_read_b128 v[200:203], v174 offset:19456
	ds_read_b128 v[204:207], v174 offset:20480
	ds_read_b128 v[208:211], v174 offset:21504
	ds_read_b128 v[212:215], v174 offset:22528
	ds_read_b128 v[216:219], v174 offset:23552
	global_load_lds_dwordx4 v[220:221], off
	s_add_i32 m0, s72, 0x2000
	s_add_u32 s72, s6, 0x18000
	v_lshl_add_u64 v[222:223], s[6:7], 0, v[136:137]
	s_addc_u32 s73, s7, 0
	s_add_i32 s74, s67, s42
	global_load_lds_dwordx4 v[222:223], off
	v_lshl_add_u64 v[224:225], s[72:73], 0, v[132:133]
	s_mov_b32 m0, s74
	v_lshl_add_u64 v[226:227], s[8:9], 0, v[134:135]
	global_load_lds_dwordx4 v[224:225], off
	v_lshl_add_u64 v[224:225], s[72:73], 0, v[136:137]
	s_add_i32 m0, s74, 0x2000
	s_nop 0
	global_load_lds_dwordx4 v[224:225], off
	v_lshl_add_u64 v[224:225], s[8:9], 0, v[130:131]
	s_mov_b32 m0, s43
	s_nop 0
	global_load_lds_dwordx4 v[224:225], off
	s_mov_b32 m0, s44
	s_nop 0
	global_load_lds_dwordx4 v[226:227], off
	s_waitcnt vmcnt(8)
	s_waitcnt lgkmcnt(0)
	s_barrier
	s_setprio 1
	s_waitcnt lgkmcnt(0)
	v_mfma_f32_16x16x32_bf16 v[62:65], v[148:151], v[188:191], 0
	v_mfma_f32_16x16x32_bf16 v[58:61], v[156:159], v[188:191], 0
	v_mfma_f32_16x16x32_bf16 v[46:49], v[148:151], v[196:199], 0
	v_mfma_f32_16x16x32_bf16 v[42:45], v[156:159], v[196:199], 0
	v_mfma_f32_16x16x32_bf16 v[30:33], v[148:151], v[204:207], 0
	v_mfma_f32_16x16x32_bf16 v[26:29], v[156:159], v[204:207], 0
	v_mfma_f32_16x16x32_bf16 v[14:17], v[148:151], v[212:215], 0
	v_mfma_f32_16x16x32_bf16 v[10:13], v[156:159], v[212:215], 0
	v_mfma_f32_16x16x32_bf16 v[62:65], v[152:155], v[192:195], v[62:65]
	v_mfma_f32_16x16x32_bf16 v[58:61], v[160:163], v[192:195], v[58:61]
	v_mfma_f32_16x16x32_bf16 v[46:49], v[152:155], v[200:203], v[46:49]
	v_mfma_f32_16x16x32_bf16 v[42:45], v[160:163], v[200:203], v[42:45]
	v_mfma_f32_16x16x32_bf16 v[30:33], v[152:155], v[208:211], v[30:33]
	v_mfma_f32_16x16x32_bf16 v[26:29], v[160:163], v[208:211], v[26:29]
	v_mfma_f32_16x16x32_bf16 v[14:17], v[152:155], v[216:219], v[14:17]
	v_mfma_f32_16x16x32_bf16 v[10:13], v[160:163], v[216:219], v[10:13]
	s_setprio 0
	s_setprio 1
	v_mfma_f32_16x16x32_bf16 v[54:57], v[164:167], v[188:191], 0
	v_mfma_f32_16x16x32_bf16 v[50:53], v[180:183], v[188:191], 0
	v_mfma_f32_16x16x32_bf16 v[38:41], v[164:167], v[196:199], 0
	v_mfma_f32_16x16x32_bf16 v[34:37], v[180:183], v[196:199], 0
	v_mfma_f32_16x16x32_bf16 v[22:25], v[164:167], v[204:207], 0
	v_mfma_f32_16x16x32_bf16 v[18:21], v[180:183], v[204:207], 0
	v_mfma_f32_16x16x32_bf16 v[6:9], v[164:167], v[212:215], 0
	v_mfma_f32_16x16x32_bf16 v[2:5], v[180:183], v[212:215], 0
	v_mfma_f32_16x16x32_bf16 v[54:57], v[176:179], v[192:195], v[54:57]
	v_mfma_f32_16x16x32_bf16 v[50:53], v[184:187], v[192:195], v[50:53]
	v_mfma_f32_16x16x32_bf16 v[38:41], v[176:179], v[200:203], v[38:41]
	v_mfma_f32_16x16x32_bf16 v[34:37], v[184:187], v[200:203], v[34:37]
	v_mfma_f32_16x16x32_bf16 v[22:25], v[176:179], v[208:211], v[22:25]
	v_mfma_f32_16x16x32_bf16 v[18:21], v[184:187], v[208:211], v[18:21]
	v_mfma_f32_16x16x32_bf16 v[6:9], v[176:179], v[216:219], v[6:9]
	v_mfma_f32_16x16x32_bf16 v[2:5], v[184:187], v[216:219], v[2:5]
	s_setprio 0
	s_barrier

; #define PG8_STAGE(bufoff, gbase, voff) do { _Pragma("unroll") for (int _i = 0; _i < 2; ++_i) \
;         __builtin_amdgcn_global_load_lds((const unsigned*)((const char*)(gbase) + (voff)[_i]), (PG8_LAS unsigned*)(lds + (bufoff) + ldsw + _i * 8192), 16, 0, 0); } while (0)
; #define PG8_LDA(dst, b, h) do { _Pragma("unroll") for (int m = 0; m < 4; ++m) _Pragma("unroll") for (int k = 0; k < 2; ++k) dst[m][k] = *(const PG8_LAS bf16x8*)(lds + PG8_SA(b, h) + aoff + m * 2048 + k * 1024); } while (0)
; #define PG8_LDB(dst, b, h) do { _Pragma("unroll") for (int n = 0; n < 2; ++n) _Pragma("unroll") for (int k = 0; k < 2; ++k) dst[n][k] = *(const PG8_LAS bf16x8*)(lds + PG8_SB(b, h) + boff + n * 2048 + k * 1024); } while (0)
; #define PG8_SCHED __builtin_amdgcn_sched_barrier(0)
; template <class Epi, class Sched, bool ALIGN_EPI = false, bool SP2 = false>
; __device__ __forceinline__ void gemm_phase(PG8_LAS unsigned char* lds, const Gemm g, const Sched& S, const Epi& E) {
;     ...
;             PG8_LDB(B0, 1, 0); PG8_LDB(B1, 1, 1); PG8_SCHED; PG8_LDA(At, 1, 0); PG8_STAGE(PG8_SA(0, 1), a2 + hstep, voffA);
	s_add_i32 s72, 0, 0x18000
	v_add_u32_e32 v138, s72, v168
	s_add_i32 s73, 0, 0x1c000
	ds_read_b128 v[148:151], v138
	ds_read_b128 v[152:155], v138 offset:1024
	ds_read_b128 v[156:159], v138 offset:2048
	ds_read_b128 v[160:163], v138 offset:3072
	v_add_u32_e32 v138, s73, v168
	ds_read_b128 v[164:167], v138
	ds_read_b128 v[176:179], v138 offset:1024
	ds_read_b128 v[180:183], v138 offset:2048
	ds_read_b128 v[184:187], v138 offset:3072

; #define PG8_STAGE(bufoff, gbase, voff) do { _Pragma("unroll") for (int _i = 0; _i < 2; ++_i) \
;         __builtin_amdgcn_global_load_lds((const unsigned*)((const char*)(gbase) + (voff)[_i]), (PG8_LAS unsigned*)(lds + (bufoff) + ldsw + _i * 8192), 16, 0, 0); } while (0)
; #define PG8_LDA(dst, b, h) do { _Pragma("unroll") for (int m = 0; m < 4; ++m) _Pragma("unroll") for (int k = 0; k < 2; ++k) dst[m][k] = *(const PG8_LAS bf16x8*)(lds + PG8_SA(b, h) + aoff + m * 2048 + k * 1024); } while (0)
; #define PG8_LDB(dst, b, h) do { _Pragma("unroll") for (int n = 0; n < 2; ++n) _Pragma("unroll") for (int k = 0; k < 2; ++k) dst[n][k] = *(const PG8_LAS bf16x8*)(lds + PG8_SB(b, h) + boff + n * 2048 + k * 1024); } while (0)
; #define PG8_MMA(ai, bj, At, Bt) do { __builtin_amdgcn_s_setprio(1); _Pragma("unroll") for (int m = 0; m < 4; ++m) _Pragma("unroll") for (int n = 0; n < 2; ++n) _Pragma("unroll") for (int k = 0; k < 2; ++k) \
;         acc[ai][bj][m][n] = __builtin_amdgcn_mfma_f32_16x16x32_bf16(Bt[n][k], At[m][k], acc[ai][bj][m][n], 0, 0, 0); __builtin_amdgcn_s_setprio(0); } while (0)
; #define PG8_WAIT_V(n) asm volatile("s_waitcnt vmcnt(" #n ")" ::: "memory")
; #define PG8_WAIT_L(n) asm volatile("s_waitcnt lgkmcnt(" #n ")" ::: "memory")
; #define PG8_BAR __builtin_amdgcn_s_barrier()
; #define PG8_SCHED __builtin_amdgcn_sched_barrier(0)
; template <class Epi, class Sched, bool ALIGN_EPI = false, bool SP2 = false>
; __device__ __forceinline__ void gemm_phase(PG8_LAS unsigned char* lds, const Gemm g, const Sched& S, const Epi& E) {
;     ...
;             PG8_LDB(B0, 1, 0); PG8_LDB(B1, 1, 1); PG8_SCHED; PG8_LDA(At, 1, 0); PG8_STAGE(PG8_SA(0, 1), a2 + hstep, voffA);
;             PG8_WAIT_V(8); PG8_WAIT_L(0); PG8_BAR; PG8_MMA(0, 0, At, B0); PG8_MMA(0, 1, At, B1); PG8_BAR; PG8_SCHED;
	s_add_u32 s8, s8, 0x18000
	s_addc_u32 s9, s9, 0
	s_mov_b32 m0, s45
	v_lshl_add_u64 v[228:229], s[8:9], 0, v[130:131]
	ds_read_b128 v[188:191], v174 offset:32768
	ds_read_b128 v[192:195], v174 offset:33792
	ds_read_b128 v[196:199], v174 offset:34816
	ds_read_b128 v[200:203], v174 offset:35840
	ds_read_b128 v[204:207], v174 offset:36864
	ds_read_b128 v[208:211], v174 offset:37888
	ds_read_b128 v[212:215], v174 offset:38912
	ds_read_b128 v[216:219], v174 offset:39936
	global_load_lds_dwordx4 v[228:229], off
	v_lshl_add_u64 v[228:229], s[8:9], 0, v[134:135]
	s_mov_b32 m0, s52
	s_nop 0
	global_load_lds_dwordx4 v[228:229], off
	s_waitcnt vmcnt(8)
	s_waitcnt lgkmcnt(0)
	s_barrier
	s_setprio 1
	s_waitcnt lgkmcnt(0)
	v_mfma_f32_16x16x32_bf16 v[126:129], v[148:151], v[188:191], v[126:129]
	v_mfma_f32_16x16x32_bf16 v[122:125], v[156:159], v[188:191], v[122:125]
	v_mfma_f32_16x16x32_bf16 v[110:113], v[148:151], v[196:199], v[110:113]
	v_mfma_f32_16x16x32_bf16 v[106:109], v[156:159], v[196:199], v[106:109]
	v_mfma_f32_16x16x32_bf16 v[94:97], v[148:151], v[204:207], v[94:97]
	v_mfma_f32_16x16x32_bf16 v[90:93], v[156:159], v[204:207], v[90:93]
	v_mfma_f32_16x16x32_bf16 v[78:81], v[148:151], v[212:215], v[78:81]
	v_mfma_f32_16x16x32_bf16 v[74:77], v[156:159], v[212:215], v[74:77]
	v_mfma_f32_16x16x32_bf16 v[126:129], v[152:155], v[192:195], v[126:129]
	v_mfma_f32_16x16x32_bf16 v[122:125], v[160:163], v[192:195], v[122:125]
	v_mfma_f32_16x16x32_bf16 v[110:113], v[152:155], v[200:203], v[110:113]
	v_mfma_f32_16x16x32_bf16 v[106:109], v[160:163], v[200:203], v[106:109]
	v_mfma_f32_16x16x32_bf16 v[94:97], v[152:155], v[208:211], v[94:97]
	v_mfma_f32_16x16x32_bf16 v[90:93], v[160:163], v[208:211], v[90:93]
	v_mfma_f32_16x16x32_bf16 v[78:81], v[152:155], v[216:219], v[78:81]
	v_mfma_f32_16x16x32_bf16 v[74:77], v[160:163], v[216:219], v[74:77]
	s_setprio 0
	s_setprio 1
	v_mfma_f32_16x16x32_bf16 v[118:121], v[164:167], v[188:191], v[118:121]
	v_mfma_f32_16x16x32_bf16 v[114:117], v[180:183], v[188:191], v[114:117]
	v_mfma_f32_16x16x32_bf16 v[102:105], v[164:167], v[196:199], v[102:105]
	v_mfma_f32_16x16x32_bf16 v[98:101], v[180:183], v[196:199], v[98:101]
	v_mfma_f32_16x16x32_bf16 v[86:89], v[164:167], v[204:207], v[86:89]
	v_mfma_f32_16x16x32_bf16 v[82:85], v[180:183], v[204:207], v[82:85]
	v_mfma_f32_16x16x32_bf16 v[70:73], v[164:167], v[212:215], v[70:73]
	v_mfma_f32_16x16x32_bf16 v[66:69], v[180:183], v[212:215], v[66:69]
	v_mfma_f32_16x16x32_bf16 v[118:121], v[176:179], v[192:195], v[118:121]
	v_mfma_f32_16x16x32_bf16 v[114:117], v[184:187], v[192:195], v[114:117]
	v_mfma_f32_16x16x32_bf16 v[102:105], v[176:179], v[200:203], v[102:105]
	v_mfma_f32_16x16x32_bf16 v[98:101], v[184:187], v[200:203], v[98:101]
	v_mfma_f32_16x16x32_bf16 v[86:89], v[176:179], v[208:211], v[86:89]
	v_mfma_f32_16x16x32_bf16 v[82:85], v[184:187], v[208:211], v[82:85]
	v_mfma_f32_16x16x32_bf16 v[70:73], v[176:179], v[216:219], v[70:73]
	v_mfma_f32_16x16x32_bf16 v[66:69], v[184:187], v[216:219], v[66:69]
	s_setprio 0
	s_barrier

; #define PG8_STAGE(bufoff, gbase, voff) do { _Pragma("unroll") for (int _i = 0; _i < 2; ++_i) \
;         __builtin_amdgcn_global_load_lds((const unsigned*)((const char*)(gbase) + (voff)[_i]), (PG8_LAS unsigned*)(lds + (bufoff) + ldsw + _i * 8192), 16, 0, 0); } while (0)
; #define PG8_LDA(dst, b, h) do { _Pragma("unroll") for (int m = 0; m < 4; ++m) _Pragma("unroll") for (int k = 0; k < 2; ++k) dst[m][k] = *(const PG8_LAS bf16x8*)(lds + PG8_SA(b, h) + aoff + m * 2048 + k * 1024); } while (0)
; #define PG8_MMA(ai, bj, At, Bt) do { __builtin_amdgcn_s_setprio(1); _Pragma("unroll") for (int m = 0; m < 4; ++m) _Pragma("unroll") for (int n = 0; n < 2; ++n) _Pragma("unroll") for (int k = 0; k < 2; ++k) \
;         acc[ai][bj][m][n] = __builtin_amdgcn_mfma_f32_16x16x32_bf16(Bt[n][k], At[m][k], acc[ai][bj][m][n], 0, 0, 0); __builtin_amdgcn_s_setprio(0); } while (0)
; #define PG8_WAIT_V(n) asm volatile("s_waitcnt vmcnt(" #n ")" ::: "memory")
; #define PG8_WAIT_L(n) asm volatile("s_waitcnt lgkmcnt(" #n ")" ::: "memory")
; #define PG8_BAR __builtin_amdgcn_s_barrier()
; #define PG8_SCHED __builtin_amdgcn_sched_barrier(0)
; template <class Epi, class Sched, bool ALIGN_EPI = false, bool SP2 = false>
; __device__ __forceinline__ void gemm_phase(PG8_LAS unsigned char* lds, const Gemm g, const Sched& S, const Epi& E) {
;     ...
;             PG8_LDA(At, 1, 1); PG8_STAGE(PG8_SB(1, 0), b3, voffB); PG8_STAGE(PG8_SB(1, 1), b3 + hstep, voffB); PG8_STAGE(PG8_SA(1, 0), a3, voffA);
;             PG8_WAIT_V(8); PG8_WAIT_L(0); PG8_BAR; PG8_MMA(1, 0, At, B0); PG8_MMA(1, 1, At, B1); PG8_BAR; PG8_SCHED;
	s_add_i32 s8, s72, s42
	v_lshl_add_u64 v[220:221], v[220:221], 0, s[14:15]
	s_mov_b32 m0, s8
	ds_read_b128 v[188:191], v174 offset:49152
	ds_read_b128 v[192:195], v174 offset:50176
	ds_read_b128 v[196:199], v174 offset:51200
	ds_read_b128 v[200:203], v174 offset:52224
	ds_read_b128 v[204:207], v174 offset:53248
	ds_read_b128 v[208:211], v174 offset:54272
	ds_read_b128 v[212:215], v174 offset:55296
	ds_read_b128 v[216:219], v174 offset:56320
	global_load_lds_dwordx4 v[220:221], off
	s_add_i32 m0, s8, 0x2000
	s_add_u32 s6, s6, 0x18080
	v_lshl_add_u64 v[220:221], v[222:223], 0, s[14:15]
	s_addc_u32 s7, s7, 0
	s_add_i32 s8, s73, s42
	global_load_lds_dwordx4 v[220:221], off
	v_lshl_add_u64 v[220:221], s[6:7], 0, v[132:133]
	s_mov_b32 m0, s8
	s_nop 0
	global_load_lds_dwordx4 v[220:221], off
	v_lshl_add_u64 v[220:221], s[6:7], 0, v[136:137]
	s_add_i32 m0, s8, 0x2000
	s_nop 0
	global_load_lds_dwordx4 v[220:221], off
	v_lshl_add_u64 v[220:221], v[224:225], 0, s[14:15]
	s_mov_b32 m0, s56
	s_nop 0
	global_load_lds_dwordx4 v[220:221], off
	v_lshl_add_u64 v[220:221], v[226:227], 0, s[14:15]
	s_mov_b32 m0, s57
	s_nop 0
	global_load_lds_dwordx4 v[220:221], off
	s_waitcnt vmcnt(8)
	s_waitcnt lgkmcnt(0)
	s_barrier
	s_setprio 1
	s_waitcnt lgkmcnt(0)
	v_mfma_f32_16x16x32_bf16 v[62:65], v[148:151], v[188:191], v[62:65]
	v_mfma_f32_16x16x32_bf16 v[58:61], v[156:159], v[188:191], v[58:61]
	v_mfma_f32_16x16x32_bf16 v[46:49], v[148:151], v[196:199], v[46:49]
	v_mfma_f32_16x16x32_bf16 v[42:45], v[156:159], v[196:199], v[42:45]
	v_mfma_f32_16x16x32_bf16 v[30:33], v[148:151], v[204:207], v[30:33]
	v_mfma_f32_16x16x32_bf16 v[26:29], v[156:159], v[204:207], v[26:29]
	v_mfma_f32_16x16x32_bf16 v[14:17], v[148:151], v[212:215], v[14:17]
	v_mfma_f32_16x16x32_bf16 v[10:13], v[156:159], v[212:215], v[10:13]
	v_mfma_f32_16x16x32_bf16 v[62:65], v[152:155], v[192:195], v[62:65]
	v_mfma_f32_16x16x32_bf16 v[58:61], v[160:163], v[192:195], v[58:61]
	v_mfma_f32_16x16x32_bf16 v[46:49], v[152:155], v[200:203], v[46:49]
	v_mfma_f32_16x16x32_bf16 v[42:45], v[160:163], v[200:203], v[42:45]
	v_mfma_f32_16x16x32_bf16 v[30:33], v[152:155], v[208:211], v[30:33]
	v_mfma_f32_16x16x32_bf16 v[26:29], v[160:163], v[208:211], v[26:29]
	v_mfma_f32_16x16x32_bf16 v[14:17], v[152:155], v[216:219], v[14:17]
	v_mfma_f32_16x16x32_bf16 v[10:13], v[160:163], v[216:219], v[10:13]
	s_setprio 0
	s_setprio 1
	v_mfma_f32_16x16x32_bf16 v[54:57], v[164:167], v[188:191], v[54:57]
	v_mfma_f32_16x16x32_bf16 v[50:53], v[180:183], v[188:191], v[50:53]
	v_mfma_f32_16x16x32_bf16 v[38:41], v[164:167], v[196:199], v[38:41]
	v_mfma_f32_16x16x32_bf16 v[34:37], v[180:183], v[196:199], v[34:37]
	v_mfma_f32_16x16x32_bf16 v[22:25], v[164:167], v[204:207], v[22:25]
	v_mfma_f32_16x16x32_bf16 v[18:21], v[180:183], v[204:207], v[18:21]
	v_mfma_f32_16x16x32_bf16 v[6:9], v[164:167], v[212:215], v[6:9]
	v_mfma_f32_16x16x32_bf16 v[2:5], v[180:183], v[212:215], v[2:5]
	v_mfma_f32_16x16x32_bf16 v[54:57], v[176:179], v[192:195], v[54:57]
	v_mfma_f32_16x16x32_bf16 v[50:53], v[184:187], v[192:195], v[50:53]
	v_mfma_f32_16x16x32_bf16 v[38:41], v[176:179], v[200:203], v[38:41]
	v_mfma_f32_16x16x32_bf16 v[34:37], v[184:187], v[200:203], v[34:37]
	v_mfma_f32_16x16x32_bf16 v[22:25], v[176:179], v[208:211], v[22:25]
	v_mfma_f32_16x16x32_bf16 v[18:21], v[184:187], v[208:211], v[18:21]
	v_mfma_f32_16x16x32_bf16 v[6:9], v[176:179], v[216:219], v[6:9]
	v_mfma_f32_16x16x32_bf16 v[2:5], v[184:187], v[216:219], v[2:5]
	s_setprio 0
	s_barrier

; #define PG8_STAGE(bufoff, gbase, voff) do { _Pragma("unroll") for (int _i = 0; _i < 2; ++_i) \
;         __builtin_amdgcn_global_load_lds((const unsigned*)((const char*)(gbase) + (voff)[_i]), (PG8_LAS unsigned*)(lds + (bufoff) + ldsw + _i * 8192), 16, 0, 0); } while (0)
; #define PG8_LDA(dst, b, h) do { _Pragma("unroll") for (int m = 0; m < 4; ++m) _Pragma("unroll") for (int k = 0; k < 2; ++k) dst[m][k] = *(const PG8_LAS bf16x8*)(lds + PG8_SA(b, h) + aoff + m * 2048 + k * 1024); } while (0)
; #define PG8_LDB(dst, b, h) do { _Pragma("unroll") for (int n = 0; n < 2; ++n) _Pragma("unroll") for (int k = 0; k < 2; ++k) dst[n][k] = *(const PG8_LAS bf16x8*)(lds + PG8_SB(b, h) + boff + n * 2048 + k * 1024); } while (0)
; #define PG8_MMA(ai, bj, At, Bt) do { __builtin_amdgcn_s_setprio(1); _Pragma("unroll") for (int m = 0; m < 4; ++m) _Pragma("unroll") for (int n = 0; n < 2; ++n) _Pragma("unroll") for (int k = 0; k < 2; ++k) \
;         acc[ai][bj][m][n] = __builtin_amdgcn_mfma_f32_16x16x32_bf16(Bt[n][k], At[m][k], acc[ai][bj][m][n], 0, 0, 0); __builtin_amdgcn_s_setprio(0); } while (0)
; #define PG8_WAIT_V(n) asm volatile("s_waitcnt vmcnt(" #n ")" ::: "memory")
; #define PG8_BAR __builtin_amdgcn_s_barrier()
; template <class Epi, class Sched, bool ALIGN_EPI = false, bool SP2 = false>
; __device__ __forceinline__ void gemm_phase(PG8_LAS unsigned char* lds, const Gemm g, const Sched& S, const Epi& E) {
;     ...
;         for (int t = 0; t < nt; t += 2) {
;             const bool last = (t == nt - 2);
;             const char* a1 = cA + (size_t)(t + 1) * kstep;
;             const char* a2 = last ? nA : cA + (size_t)(t + 2) * kstep; const char* b2 = last ? nB : cB + (size_t)(t + 2) * kstep;
;             const char* a3 = a2 + kstep; const char* b3 = b2 + kstep;
;             if (last && has_next) S.a_ready(nxt);
;             if constexpr (SP2) {
;             PG8_LDB(B0, 0, 0); PG8_LDB(B1, 0, 1); PG8_SCHED; PG8_LDA(At, 0, 0); PG8_STAGE(PG8_SA(1, 1), a1 + hstep, voffA);
;             PG8_WAIT_V(8); PG8_WAIT_L(0); PG8_BAR; PG8_MMA(0, 0, At, B0); PG8_MMA(0, 1, At, B1); PG8_BAR; PG8_SCHED;
;             PG8_LDA(At, 0, 1); PG8_STAGE(PG8_SB(0, 0), b2, voffB); PG8_STAGE(PG8_SB(0, 1), b2 + hstep, voffB); PG8_STAGE(PG8_SA(0, 0), a2, voffA);
;             PG8_WAIT_V(8); PG8_WAIT_L(0); PG8_BAR; PG8_MMA(1, 0, At, B0); PG8_MMA(1, 1, At, B1); PG8_BAR; PG8_SCHED;
	s_add_i32 s71, s71, 2
	s_add_u32 s4, s4, 0x100
	s_addc_u32 s5, s5, 0
	s_add_u32 s35, s35, 0x100
	s_addc_u32 s70, s70, 0
	s_cmp_ge_i32 s71, s98
	s_cbranch_scc1 .Lp7_kloop_done
.LBB0_865:
	ds_read_b128 v[148:151], v170
	ds_read_b128 v[152:155], v170 offset:1024
	ds_read_b128 v[156:159], v170 offset:2048
	ds_read_b128 v[160:163], v170 offset:3072
	ds_read_b128 v[164:167], v171
	ds_read_b128 v[176:179], v171 offset:1024
	ds_read_b128 v[180:183], v171 offset:2048
	ds_read_b128 v[184:187], v171 offset:3072
	s_add_u32 s6, s4, 0xfffe8080
	s_addc_u32 s7, s5, -1
	s_cmp_eq_u32 s71, s101
	s_cselect_b32 s9, s29, s7
	s_cselect_b32 s8, s28, s6
	s_cselect_b32 s7, s31, s70
	s_cselect_b32 s6, s30, s35
	v_lshl_add_u64 v[220:221], s[4:5], 0, v[140:141]
	s_add_i32 m0, s43, 0xc000
	ds_read_b128 v[188:191], v174
	ds_read_b128 v[192:195], v174 offset:1024
	ds_read_b128 v[196:199], v174 offset:2048
	ds_read_b128 v[200:203], v174 offset:3072
	ds_read_b128 v[204:207], v174 offset:4096
	ds_read_b128 v[208:211], v174 offset:5120
	ds_read_b128 v[212:215], v174 offset:6144
	ds_read_b128 v[216:219], v174 offset:7168
	global_load_lds_dwordx4 v[220:221], off
	v_lshl_add_u64 v[220:221], s[4:5], 0, v[142:143]
	s_add_i32 m0, s43, 0xe000
	s_nop 0
	global_load_lds_dwordx4 v[220:221], off
	s_waitcnt vmcnt(8)
	s_waitcnt lgkmcnt(0)
	s_barrier
	s_setprio 1
	s_waitcnt lgkmcnt(0)
	v_mfma_f32_16x16x32_bf16 v[126:129], v[148:151], v[188:191], v[126:129]
	v_mfma_f32_16x16x32_bf16 v[122:125], v[156:159], v[188:191], v[122:125]
	v_mfma_f32_16x16x32_bf16 v[110:113], v[148:151], v[196:199], v[110:113]
	v_mfma_f32_16x16x32_bf16 v[106:109], v[156:159], v[196:199], v[106:109]
	v_mfma_f32_16x16x32_bf16 v[94:97], v[148:151], v[204:207], v[94:97]
	v_mfma_f32_16x16x32_bf16 v[90:93], v[156:159], v[204:207], v[90:93]
	v_mfma_f32_16x16x32_bf16 v[78:81], v[148:151], v[212:215], v[78:81]
	v_mfma_f32_16x16x32_bf16 v[74:77], v[156:159], v[212:215], v[74:77]
	v_mfma_f32_16x16x32_bf16 v[126:129], v[152:155], v[192:195], v[126:129]
	v_mfma_f32_16x16x32_bf16 v[122:125], v[160:163], v[192:195], v[122:125]
	v_mfma_f32_16x16x32_bf16 v[110:113], v[152:155], v[200:203], v[110:113]
	v_mfma_f32_16x16x32_bf16 v[106:109], v[160:163], v[200:203], v[106:109]
	v_mfma_f32_16x16x32_bf16 v[94:97], v[152:155], v[208:211], v[94:97]
	v_mfma_f32_16x16x32_bf16 v[90:93], v[160:163], v[208:211], v[90:93]
	v_mfma_f32_16x16x32_bf16 v[78:81], v[152:155], v[216:219], v[78:81]
	v_mfma_f32_16x16x32_bf16 v[74:77], v[160:163], v[216:219], v[74:77]
	s_setprio 0
	s_setprio 1
	v_mfma_f32_16x16x32_bf16 v[118:121], v[164:167], v[188:191], v[118:121]
	v_mfma_f32_16x16x32_bf16 v[114:117], v[180:183], v[188:191], v[114:117]
	v_mfma_f32_16x16x32_bf16 v[102:105], v[164:167], v[196:199], v[102:105]
	v_mfma_f32_16x16x32_bf16 v[98:101], v[180:183], v[196:199], v[98:101]
	v_mfma_f32_16x16x32_bf16 v[86:89], v[164:167], v[204:207], v[86:89]
	v_mfma_f32_16x16x32_bf16 v[82:85], v[180:183], v[204:207], v[82:85]
	v_mfma_f32_16x16x32_bf16 v[70:73], v[164:167], v[212:215], v[70:73]
	v_mfma_f32_16x16x32_bf16 v[66:69], v[180:183], v[212:215], v[66:69]
	v_mfma_f32_16x16x32_bf16 v[118:121], v[176:179], v[192:195], v[118:121]
	v_mfma_f32_16x16x32_bf16 v[114:117], v[184:187], v[192:195], v[114:117]
	v_mfma_f32_16x16x32_bf16 v[102:105], v[176:179], v[200:203], v[102:105]
	v_mfma_f32_16x16x32_bf16 v[98:101], v[184:187], v[200:203], v[98:101]
	v_mfma_f32_16x16x32_bf16 v[86:89], v[176:179], v[208:211], v[86:89]
	v_mfma_f32_16x16x32_bf16 v[82:85], v[184:187], v[208:211], v[82:85]
	v_mfma_f32_16x16x32_bf16 v[70:73], v[176:179], v[216:219], v[70:73]
	v_mfma_f32_16x16x32_bf16 v[66:69], v[184:187], v[216:219], v[66:69]
	s_setprio 0
	s_barrier
	s_add_i32 s72, s66, s42
	v_lshl_add_u64 v[220:221], s[6:7], 0, v[132:133]
	s_mov_b32 m0, s72
	ds_read_b128 v[188:191], v174 offset:16384
	ds_read_b128 v[192:195], v174 offset:17408
	ds_read_b128 v[196:199], v174 offset:18432
	ds_read_b128 v[200:203], v174 offset:19456
	ds_read_b128 v[204:207], v174 offset:20480
	ds_read_b128 v[208:211], v174 offset:21504
	ds_read_b128 v[212:215], v174 offset:22528
	ds_read_b128 v[216:219], v174 offset:23552
	global_load_lds_dwordx4 v[220:221], off
	s_add_i32 m0, s72, 0x2000
	s_add_u32 s72, s6, 0x18000
	v_lshl_add_u64 v[222:223], s[6:7], 0, v[136:137]
	s_addc_u32 s73, s7, 0
	s_add_i32 s74, s67, s42
	global_load_lds_dwordx4 v[222:223], off
	v_lshl_add_u64 v[224:225], s[72:73], 0, v[132:133]
	s_mov_b32 m0, s74
	v_lshl_add_u64 v[226:227], s[8:9], 0, v[134:135]
	global_load_lds_dwordx4 v[224:225], off
	v_lshl_add_u64 v[224:225], s[72:73], 0, v[136:137]
	s_add_i32 m0, s74, 0x2000
	s_nop 0
	global_load_lds_dwordx4 v[224:225], off
	v_lshl_add_u64 v[224:225], s[8:9], 0, v[130:131]
	s_mov_b32 m0, s43
	s_nop 0
	global_load_lds_dwordx4 v[224:225], off
	s_mov_b32 m0, s44
	s_nop 0
	global_load_lds_dwordx4 v[226:227], off
	s_waitcnt vmcnt(8)
	s_waitcnt lgkmcnt(0)
	s_barrier
; #define PG8_STAGE(bufoff, gbase, voff) do { _Pragma("unroll") for (int _i = 0; _i < 2; ++_i) \
;         __builtin_amdgcn_global_load_lds((const unsigned*)((const char*)(gbase) + (voff)[_i]), (PG8_LAS unsigned*)(lds + (bufoff) + ldsw + _i * 8192), 16, 0, 0); } while (0)
; #define PG8_LDA(dst, b, h) do { _Pragma("unroll") for (int m = 0; m < 4; ++m) _Pragma("unroll") for (int k = 0; k < 2; ++k) dst[m][k] = *(const PG8_LAS bf16x8*)(lds + PG8_SA(b, h) + aoff + m * 2048 + k * 1024); } while (0)
; #define PG8_LDB(dst, b, h) do { _Pragma("unroll") for (int n = 0; n < 2; ++n) _Pragma("unroll") for (int k = 0; k < 2; ++k) dst[n][k] = *(const PG8_LAS bf16x8*)(lds + PG8_SB(b, h) + boff + n * 2048 + k * 1024); } while (0)
; #define PG8_MMA(ai, bj, At, Bt) do { __builtin_amdgcn_s_setprio(1); _Pragma("unroll") for (int m = 0; m < 4; ++m) _Pragma("unroll") for (int n = 0; n < 2; ++n) _Pragma("unroll") for (int k = 0; k < 2; ++k) \
;         acc[ai][bj][m][n] = __builtin_amdgcn_mfma_f32_16x16x32_bf16(Bt[n][k], At[m][k], acc[ai][bj][m][n], 0, 0, 0); __builtin_amdgcn_s_setprio(0); } while (0)
; #define PG8_WAIT_V(n) asm volatile("s_waitcnt vmcnt(" #n ")" ::: "memory")
; #define PG8_WAIT_L(n) asm volatile("s_waitcnt lgkmcnt(" #n ")" ::: "memory")
; #define PG8_BAR __builtin_amdgcn_s_barrier()
; #define PG8_SCHED __builtin_amdgcn_sched_barrier(0)
; template <class Epi, class Sched, bool ALIGN_EPI = false, bool SP2 = false>
; __device__ __forceinline__ void gemm_phase(PG8_LAS unsigned char* lds, const Gemm g, const Sched& S, const Epi& E) {
;     ...
;             PG8_WAIT_V(8); PG8_WAIT_L(0); PG8_BAR; PG8_MMA(1, 0, At, B0); PG8_MMA(1, 1, At, B1); PG8_BAR; PG8_SCHED;
;             PG8_LDB(B0, 1, 0); PG8_LDB(B1, 1, 1); PG8_SCHED; PG8_LDA(At, 1, 0); PG8_STAGE(PG8_SA(0, 1), a2 + hstep, voffA);
;             PG8_WAIT_V(8); PG8_WAIT_L(0); PG8_BAR; PG8_MMA(0, 0, At, B0); PG8_MMA(0, 1, At, B1); PG8_BAR; PG8_SCHED;
	s_setprio 1
	s_waitcnt lgkmcnt(0)
	v_mfma_f32_16x16x32_bf16 v[62:65], v[148:151], v[188:191], v[62:65]
	v_mfma_f32_16x16x32_bf16 v[58:61], v[156:159], v[188:191], v[58:61]
	v_mfma_f32_16x16x32_bf16 v[46:49], v[148:151], v[196:199], v[46:49]
	v_mfma_f32_16x16x32_bf16 v[42:45], v[156:159], v[196:199], v[42:45]
	v_mfma_f32_16x16x32_bf16 v[30:33], v[148:151], v[204:207], v[30:33]
	v_mfma_f32_16x16x32_bf16 v[26:29], v[156:159], v[204:207], v[26:29]
	v_mfma_f32_16x16x32_bf16 v[14:17], v[148:151], v[212:215], v[14:17]
	v_mfma_f32_16x16x32_bf16 v[10:13], v[156:159], v[212:215], v[10:13]
	v_mfma_f32_16x16x32_bf16 v[62:65], v[152:155], v[192:195], v[62:65]
	v_mfma_f32_16x16x32_bf16 v[58:61], v[160:163], v[192:195], v[58:61]
	v_mfma_f32_16x16x32_bf16 v[46:49], v[152:155], v[200:203], v[46:49]
	v_mfma_f32_16x16x32_bf16 v[42:45], v[160:163], v[200:203], v[42:45]
	v_mfma_f32_16x16x32_bf16 v[30:33], v[152:155], v[208:211], v[30:33]
	v_mfma_f32_16x16x32_bf16 v[26:29], v[160:163], v[208:211], v[26:29]
	v_mfma_f32_16x16x32_bf16 v[14:17], v[152:155], v[216:219], v[14:17]
	v_mfma_f32_16x16x32_bf16 v[10:13], v[160:163], v[216:219], v[10:13]
	s_setprio 0
	s_setprio 1
	v_mfma_f32_16x16x32_bf16 v[54:57], v[164:167], v[188:191], v[54:57]
	v_mfma_f32_16x16x32_bf16 v[50:53], v[180:183], v[188:191], v[50:53]
	v_mfma_f32_16x16x32_bf16 v[38:41], v[164:167], v[196:199], v[38:41]
	v_mfma_f32_16x16x32_bf16 v[34:37], v[180:183], v[196:199], v[34:37]
	v_mfma_f32_16x16x32_bf16 v[22:25], v[164:167], v[204:207], v[22:25]
	v_mfma_f32_16x16x32_bf16 v[18:21], v[180:183], v[204:207], v[18:21]
	v_mfma_f32_16x16x32_bf16 v[6:9], v[164:167], v[212:215], v[6:9]
	v_mfma_f32_16x16x32_bf16 v[2:5], v[180:183], v[212:215], v[2:5]
	v_mfma_f32_16x16x32_bf16 v[54:57], v[176:179], v[192:195], v[54:57]
	v_mfma_f32_16x16x32_bf16 v[50:53], v[184:187], v[192:195], v[50:53]
	v_mfma_f32_16x16x32_bf16 v[38:41], v[176:179], v[200:203], v[38:41]
	v_mfma_f32_16x16x32_bf16 v[34:37], v[184:187], v[200:203], v[34:37]
	v_mfma_f32_16x16x32_bf16 v[22:25], v[176:179], v[208:211], v[22:25]
	v_mfma_f32_16x16x32_bf16 v[18:21], v[184:187], v[208:211], v[18:21]
	v_mfma_f32_16x16x32_bf16 v[6:9], v[176:179], v[216:219], v[6:9]
	v_mfma_f32_16x16x32_bf16 v[2:5], v[184:187], v[216:219], v[2:5]
	s_setprio 0
	s_barrier
	s_add_i32 s72, 0, 0x18000
	v_add_u32_e32 v138, s72, v168
	s_add_i32 s73, 0, 0x1c000
	ds_read_b128 v[148:151], v138
	ds_read_b128 v[152:155], v138 offset:1024
	ds_read_b128 v[156:159], v138 offset:2048
	ds_read_b128 v[160:163], v138 offset:3072
	v_add_u32_e32 v138, s73, v168
	ds_read_b128 v[164:167], v138
	ds_read_b128 v[176:179], v138 offset:1024
	ds_read_b128 v[180:183], v138 offset:2048
	ds_read_b128 v[184:187], v138 offset:3072
	s_add_u32 s8, s8, 0x18000
	s_addc_u32 s9, s9, 0
	s_mov_b32 m0, s45
	v_lshl_add_u64 v[228:229], s[8:9], 0, v[130:131]
	ds_read_b128 v[188:191], v174 offset:32768
	ds_read_b128 v[192:195], v174 offset:33792
	ds_read_b128 v[196:199], v174 offset:34816
	ds_read_b128 v[200:203], v174 offset:35840
	ds_read_b128 v[204:207], v174 offset:36864
	ds_read_b128 v[208:211], v174 offset:37888
	ds_read_b128 v[212:215], v174 offset:38912
	ds_read_b128 v[216:219], v174 offset:39936
	global_load_lds_dwordx4 v[228:229], off
	v_lshl_add_u64 v[228:229], s[8:9], 0, v[134:135]
	s_mov_b32 m0, s52
	s_nop 0
	global_load_lds_dwordx4 v[228:229], off
	s_waitcnt vmcnt(8)
	s_waitcnt lgkmcnt(0)
	s_barrier
	s_setprio 1
	s_waitcnt lgkmcnt(0)
	v_mfma_f32_16x16x32_bf16 v[126:129], v[148:151], v[188:191], v[126:129]
	v_mfma_f32_16x16x32_bf16 v[122:125], v[156:159], v[188:191], v[122:125]
	v_mfma_f32_16x16x32_bf16 v[110:113], v[148:151], v[196:199], v[110:113]
	v_mfma_f32_16x16x32_bf16 v[106:109], v[156:159], v[196:199], v[106:109]
	v_mfma_f32_16x16x32_bf16 v[94:97], v[148:151], v[204:207], v[94:97]
	v_mfma_f32_16x16x32_bf16 v[90:93], v[156:159], v[204:207], v[90:93]
	v_mfma_f32_16x16x32_bf16 v[78:81], v[148:151], v[212:215], v[78:81]
	v_mfma_f32_16x16x32_bf16 v[74:77], v[156:159], v[212:215], v[74:77]
	v_mfma_f32_16x16x32_bf16 v[126:129], v[152:155], v[192:195], v[126:129]
	v_mfma_f32_16x16x32_bf16 v[122:125], v[160:163], v[192:195], v[122:125]
	v_mfma_f32_16x16x32_bf16 v[110:113], v[152:155], v[200:203], v[110:113]
	v_mfma_f32_16x16x32_bf16 v[106:109], v[160:163], v[200:203], v[106:109]
	v_mfma_f32_16x16x32_bf16 v[94:97], v[152:155], v[208:211], v[94:97]
	v_mfma_f32_16x16x32_bf16 v[90:93], v[160:163], v[208:211], v[90:93]
	v_mfma_f32_16x16x32_bf16 v[78:81], v[152:155], v[216:219], v[78:81]
	v_mfma_f32_16x16x32_bf16 v[74:77], v[160:163], v[216:219], v[74:77]
	s_setprio 0
	s_setprio 1
	v_mfma_f32_16x16x32_bf16 v[118:121], v[164:167], v[188:191], v[118:121]
	v_mfma_f32_16x16x32_bf16 v[114:117], v[180:183], v[188:191], v[114:117]
	v_mfma_f32_16x16x32_bf16 v[102:105], v[164:167], v[196:199], v[102:105]
	v_mfma_f32_16x16x32_bf16 v[98:101], v[180:183], v[196:199], v[98:101]
	v_mfma_f32_16x16x32_bf16 v[86:89], v[164:167], v[204:207], v[86:89]
	v_mfma_f32_16x16x32_bf16 v[82:85], v[180:183], v[204:207], v[82:85]
	v_mfma_f32_16x16x32_bf16 v[70:73], v[164:167], v[212:215], v[70:73]
	v_mfma_f32_16x16x32_bf16 v[66:69], v[180:183], v[212:215], v[66:69]
	v_mfma_f32_16x16x32_bf16 v[118:121], v[176:179], v[192:195], v[118:121]
	v_mfma_f32_16x16x32_bf16 v[114:117], v[184:187], v[192:195], v[114:117]
	v_mfma_f32_16x16x32_bf16 v[102:105], v[176:179], v[200:203], v[102:105]
	v_mfma_f32_16x16x32_bf16 v[98:101], v[184:187], v[200:203], v[98:101]
	v_mfma_f32_16x16x32_bf16 v[86:89], v[176:179], v[208:211], v[86:89]
	v_mfma_f32_16x16x32_bf16 v[82:85], v[184:187], v[208:211], v[82:85]
	v_mfma_f32_16x16x32_bf16 v[70:73], v[176:179], v[216:219], v[70:73]
	v_mfma_f32_16x16x32_bf16 v[66:69], v[184:187], v[216:219], v[66:69]
	s_setprio 0
	s_barrier
; #define PG8_STAGE(bufoff, gbase, voff) do { _Pragma("unroll") for (int _i = 0; _i < 2; ++_i) \
;         __builtin_amdgcn_global_load_lds((const unsigned*)((const char*)(gbase) + (voff)[_i]), (PG8_LAS unsigned*)(lds + (bufoff) + ldsw + _i * 8192), 16, 0, 0); } while (0)
; #define PG8_LDA(dst, b, h) do { _Pragma("unroll") for (int m = 0; m < 4; ++m) _Pragma("unroll") for (int k = 0; k < 2; ++k) dst[m][k] = *(const PG8_LAS bf16x8*)(lds + PG8_SA(b, h) + aoff + m * 2048 + k * 1024); } while (0)
; #define PG8_MMA(ai, bj, At, Bt) do { __builtin_amdgcn_s_setprio(1); _Pragma("unroll") for (int m = 0; m < 4; ++m) _Pragma("unroll") for (int n = 0; n < 2; ++n) _Pragma("unroll") for (int k = 0; k < 2; ++k) \
;         acc[ai][bj][m][n] = __builtin_amdgcn_mfma_f32_16x16x32_bf16(Bt[n][k], At[m][k], acc[ai][bj][m][n], 0, 0, 0); __builtin_amdgcn_s_setprio(0); } while (0)
; #define PG8_WAIT_V(n) asm volatile("s_waitcnt vmcnt(" #n ")" ::: "memory")
; #define PG8_WAIT_L(n) asm volatile("s_waitcnt lgkmcnt(" #n ")" ::: "memory")
; #define PG8_BAR __builtin_amdgcn_s_barrier()
; #define PG8_SCHED __builtin_amdgcn_sched_barrier(0)
; template <class Epi, class Sched, bool ALIGN_EPI = false, bool SP2 = false>
; __device__ __forceinline__ void gemm_phase(PG8_LAS unsigned char* lds, const Gemm g, const Sched& S, const Epi& E) {
;     ...
;             PG8_WAIT_V(8); PG8_WAIT_L(0); PG8_BAR; PG8_MMA(0, 0, At, B0); PG8_MMA(0, 1, At, B1); PG8_BAR; PG8_SCHED;
;             PG8_LDA(At, 1, 1); PG8_STAGE(PG8_SB(1, 0), b3, voffB); PG8_STAGE(PG8_SB(1, 1), b3 + hstep, voffB); PG8_STAGE(PG8_SA(1, 0), a3, voffA);
;             PG8_WAIT_V(8); PG8_WAIT_L(0); PG8_BAR; PG8_MMA(1, 0, At, B0); PG8_MMA(1, 1, At, B1); PG8_BAR; PG8_SCHED;
;     ...
;         if constexpr (ALIGN_EPI) { if (wr == 0) PG8_BAR; }
	s_add_i32 s8, s72, s42
	v_lshl_add_u64 v[220:221], v[220:221], 0, s[14:15]
	s_mov_b32 m0, s8
	ds_read_b128 v[188:191], v174 offset:49152
	ds_read_b128 v[192:195], v174 offset:50176
	ds_read_b128 v[196:199], v174 offset:51200
	ds_read_b128 v[200:203], v174 offset:52224
	ds_read_b128 v[204:207], v174 offset:53248
	ds_read_b128 v[208:211], v174 offset:54272
	ds_read_b128 v[212:215], v174 offset:55296
	ds_read_b128 v[216:219], v174 offset:56320
	global_load_lds_dwordx4 v[220:221], off
	s_add_i32 m0, s8, 0x2000
	s_add_u32 s6, s6, 0x18080
	v_lshl_add_u64 v[220:221], v[222:223], 0, s[14:15]
	s_addc_u32 s7, s7, 0
	s_add_i32 s8, s73, s42
	global_load_lds_dwordx4 v[220:221], off
	v_lshl_add_u64 v[220:221], s[6:7], 0, v[132:133]
	s_mov_b32 m0, s8
	s_nop 0
	global_load_lds_dwordx4 v[220:221], off
	v_lshl_add_u64 v[220:221], s[6:7], 0, v[136:137]
	s_add_i32 m0, s8, 0x2000
	s_nop 0
	global_load_lds_dwordx4 v[220:221], off
	v_lshl_add_u64 v[220:221], v[224:225], 0, s[14:15]
	s_mov_b32 m0, s56
	s_nop 0
	global_load_lds_dwordx4 v[220:221], off
	v_lshl_add_u64 v[220:221], v[226:227], 0, s[14:15]
	s_mov_b32 m0, s57
	s_nop 0
	global_load_lds_dwordx4 v[220:221], off
	s_waitcnt vmcnt(8)
	s_waitcnt lgkmcnt(0)
	s_barrier
	s_setprio 1
	s_waitcnt lgkmcnt(0)
	v_mfma_f32_16x16x32_bf16 v[62:65], v[148:151], v[188:191], v[62:65]
	v_mfma_f32_16x16x32_bf16 v[58:61], v[156:159], v[188:191], v[58:61]
	v_mfma_f32_16x16x32_bf16 v[46:49], v[148:151], v[196:199], v[46:49]
	v_mfma_f32_16x16x32_bf16 v[42:45], v[156:159], v[196:199], v[42:45]
	v_mfma_f32_16x16x32_bf16 v[30:33], v[148:151], v[204:207], v[30:33]
	v_mfma_f32_16x16x32_bf16 v[26:29], v[156:159], v[204:207], v[26:29]
	v_mfma_f32_16x16x32_bf16 v[14:17], v[148:151], v[212:215], v[14:17]
	v_mfma_f32_16x16x32_bf16 v[10:13], v[156:159], v[212:215], v[10:13]
	v_mfma_f32_16x16x32_bf16 v[62:65], v[152:155], v[192:195], v[62:65]
	v_mfma_f32_16x16x32_bf16 v[58:61], v[160:163], v[192:195], v[58:61]
	v_mfma_f32_16x16x32_bf16 v[46:49], v[152:155], v[200:203], v[46:49]
	v_mfma_f32_16x16x32_bf16 v[42:45], v[160:163], v[200:203], v[42:45]
	v_mfma_f32_16x16x32_bf16 v[30:33], v[152:155], v[208:211], v[30:33]
	v_mfma_f32_16x16x32_bf16 v[26:29], v[160:163], v[208:211], v[26:29]
	v_mfma_f32_16x16x32_bf16 v[14:17], v[152:155], v[216:219], v[14:17]
	v_mfma_f32_16x16x32_bf16 v[10:13], v[160:163], v[216:219], v[10:13]
	s_setprio 0
	s_setprio 1
	v_mfma_f32_16x16x32_bf16 v[54:57], v[164:167], v[188:191], v[54:57]
	v_mfma_f32_16x16x32_bf16 v[50:53], v[180:183], v[188:191], v[50:53]
	v_mfma_f32_16x16x32_bf16 v[38:41], v[164:167], v[196:199], v[38:41]
	v_mfma_f32_16x16x32_bf16 v[34:37], v[180:183], v[196:199], v[34:37]
	v_mfma_f32_16x16x32_bf16 v[22:25], v[164:167], v[204:207], v[22:25]
	v_mfma_f32_16x16x32_bf16 v[18:21], v[180:183], v[204:207], v[18:21]
	v_mfma_f32_16x16x32_bf16 v[6:9], v[164:167], v[212:215], v[6:9]
	v_mfma_f32_16x16x32_bf16 v[2:5], v[180:183], v[212:215], v[2:5]
	v_mfma_f32_16x16x32_bf16 v[54:57], v[176:179], v[192:195], v[54:57]
	v_mfma_f32_16x16x32_bf16 v[50:53], v[184:187], v[192:195], v[50:53]
	v_mfma_f32_16x16x32_bf16 v[38:41], v[176:179], v[200:203], v[38:41]
	v_mfma_f32_16x16x32_bf16 v[34:37], v[184:187], v[200:203], v[34:37]
	v_mfma_f32_16x16x32_bf16 v[22:25], v[176:179], v[208:211], v[22:25]
	v_mfma_f32_16x16x32_bf16 v[18:21], v[184:187], v[208:211], v[18:21]
	v_mfma_f32_16x16x32_bf16 v[6:9], v[176:179], v[216:219], v[6:9]
	v_mfma_f32_16x16x32_bf16 v[2:5], v[184:187], v[216:219], v[2:5]
	s_setprio 0
	s_barrier
	s_add_i32 s71, s71, 2
	s_add_u32 s4, s4, 0x100
	s_addc_u32 s5, s5, 0
	s_add_u32 s35, s35, 0x100
	s_addc_u32 s70, s70, 0
	s_cmp_ge_i32 s71, s98
	s_cbranch_scc0 .LBB0_865
.Lp7_kloop_done:
	s_and_b64 vcc, exec, s[16:17]
	s_cbranch_vccz .LBB0_868
	s_barrier
